# phase-0 static work rebalancing: adaLN blocks 0..191 take 2 short items instead of 3, the remaining short items dealt over blocks 192..511; empty block-mean iterations removed
# speedup vs baseline: 1.0053x; 1.0045x over previous
; DI int opaque(int v) { asm volatile("" : "+v"(v)); return v; }
;     for (int it = blockIdx.x; it < P0_ITEMS; it += gridDim.x) {
;         const int t = opaque(threadIdx.x);
;         int r = it;
;         if (r < P0_ADA) { if (msk & 1) ada_item(p, r, sm); continue; } r -= P0_ADA;
;         if (r < P0_KMS) { if (msk & 2) kmean_item(p.cache_m, p.page_table, r >> 5, r & 31, (float*)(p.ws + WS_KMS) + (size_t)r * 512, sm); continue; } r -= P0_KMS;
;         if (r < P0_TWIN + P0_TWOUT + 2 * P0_W1 + 2 * P0_W2) { if (!(msk & 4)) continue; } else if (!(msk & 8)) continue;
.LBB0_5:
	s_or_b64 exec, exec, s[2:3]
	s_load_dwordx16 s[16:31], s[0:1], 0x40
	v_writelane_b32 v254, s80, 8
	s_cmpk_gt_i32 s80, 0xab0
	v_writelane_b32 v254, s81, 9
	s_cbranch_scc1 .LBB0_115
	s_add_u32 s8, s0, 0xb0
	s_addc_u32 s9, s1, 0
	s_add_u32 s76, s60, 0xa240000
	s_addc_u32 s88, s61, 0
	s_add_u32 s10, s62, 0xb32000
	s_addc_u32 s11, s63, 0
	s_add_u32 s12, s62, 0xb2e000
	s_addc_u32 s13, s63, 0
	s_add_u32 s34, s62, 0xaae000
	s_addc_u32 s35, s63, 0
	s_add_u32 s64, s62, 0xa2e000
	s_addc_u32 s65, s63, 0
	s_add_u32 s66, s62, 0x82e000
	s_addc_u32 s67, s63, 0
	s_add_u32 s68, s62, 0x6e000
	s_addc_u32 s69, s63, 0
	s_add_u32 s33, s62, 0xbb6000
	s_addc_u32 s90, s63, 0
	s_cmp_lg_u64 s[50:51], 0
	s_cselect_b64 s[70:71], -1, 0
	s_add_u32 s72, s62, 0x8000
	s_addc_u32 s73, s63, 0
	s_add_u32 s77, s62, 0x7fa000
	s_addc_u32 s78, s63, 0
	s_add_u32 s82, s62, 0x177b9000
	s_addc_u32 s83, s63, 0
	s_waitcnt lgkmcnt(0)
	s_add_u32 s16, s16, 0x2d0000
	v_mov_b32_e32 v19, 0
	s_addc_u32 s17, s17, 0
	s_movk_i32 s84, 0x400
	s_movk_i32 s85, 0x2ff
	v_mov_b32_e32 v88, v19
	v_mov_b32_e32 v89, v19
	v_mov_b32_e32 v90, v19
	v_mov_b32_e32 v91, v19
	v_mov_b32_e32 v63, 0xf149f2ca
	v_mov_b64_e32 v[20:21], 0x1000
	v_mov_b64_e32 v[22:23], 0x2000
	v_mov_b64_e32 v[24:25], 0x3000
	v_mov_b32_e32 v92, v19
	v_mov_b32_e32 v93, v19
	s_movk_i32 s89, 0x104
	s_movk_i32 s86, 0x80
	s_movk_i32 s91, 0xf18
	s_movk_i32 s92, 0x3c60
	s_movk_i32 s93, 0x4000
	s_mov_b32 s94, 0x8000
	s_mov_b32 s95, 0xc000
	s_movk_i32 s96, 0x90
	s_add_i32 s75, s80, 0x580
	s_cmpk_lt_u32 s80, 0xc0
	s_cselect_b32 s97, s80, s75
	s_mov_b32 s75, 0
	s_branch .LBB0_9

;     for (int it = blockIdx.x; it < P0_ITEMS; it += gridDim.x) {
.LBB0_8:
	v_readlane_b32 s2, v254, 8
	s_waitcnt lgkmcnt(0)
	s_nop 1
	s_cmpk_lt_u32 s2, 0xc0
	s_cbranch_scc0 .Lp0_other
	s_cmpk_lt_u32 s97, 0xc0
	s_cbranch_scc0 .Lp0_ada2
	s_addk_i32 s97, 0x4c0
	s_branch .LBB0_9
.Lp0_ada2:
	s_cmpk_lt_u32 s97, 0x580
	s_cbranch_scc0 .LBB0_115
	s_addk_i32 s97, 0xc0
	s_branch .LBB0_9
.Lp0_other:
	s_addk_i32 s97, 0x140
	s_cmpk_lt_i32 s97, 0xab1
	s_cbranch_scc0 .LBB0_115
